# P5 out-proj: residual (x) tile lines touched once during the third-from-last K iteration so the E_RES epilogue reads hit cache
# baseline (speedup 1.0000x reference)
.LBB0_831:
	s_cmp_lg_u32 s71, 8
	s_cbranch_scc1 .Lwarm5_skip
	v_add_u32_e32 v240, s86, v205
	v_lshrrev_b32_e32 v241, 1, v240
	v_lshl_add_u32 v241, s52, 8, v241
	v_and_b32_e32 v240, 1, v240
	v_lshlrev_b32_e32 v240, 9, v240
	v_lshl_add_u32 v240, s50, 10, v240
	v_lshl_add_u32 v240, v241, 12, v240
	global_load_dword v241, v240, s[14:15]
	global_load_dword v241, v240, s[14:15] offset:128
	global_load_dword v241, v240, s[14:15] offset:256
	global_load_dword v241, v240, s[14:15] offset:384
